# group-barrier poll loops with s_sleep 24 between polls
# speedup vs baseline: 1.0022x; 1.0022x over previous
; __device__ __forceinline__ unsigned xb_ld(unsigned* p)              { return __hip_atomic_load(p, __ATOMIC_RELAXED, __HIP_MEMORY_SCOPE_AGENT); }
; __device__ __forceinline__ void grp_barrier(unsigned* cntw, unsigned* tmo) {
;     ...
;         while (xb_ld(cntw) < target) { __builtin_amdgcn_s_sleep(1);
;             if ((++sp & 255u) == 0u) { if (xb_ld(tmo)) break; if (sp > XB_SPIN_CAP) { atomicAdd(tmo, 1u); break; } } }
.LBB0_461:
	s_and_b32 s28, s11, 0xff
	s_mov_b64 s[26:27], -1
	s_cmp_lg_u32 s28, 0
	s_mov_b64 s[40:41], -1
	s_sleep 24
	s_cbranch_scc0 .LBB0_464
	s_and_b64 vcc, exec, s[40:41]
	s_cbranch_vccz .LBB0_460

; __device__ __forceinline__ unsigned xb_ld(unsigned* p)              { return __hip_atomic_load(p, __ATOMIC_RELAXED, __HIP_MEMORY_SCOPE_AGENT); }
; __device__ __forceinline__ void grp_barrier(unsigned* cntw, unsigned* tmo) {
;     ...
;         while (xb_ld(cntw) < target) { __builtin_amdgcn_s_sleep(1);
;             if ((++sp & 255u) == 0u) { if (xb_ld(tmo)) break; if (sp > XB_SPIN_CAP) { atomicAdd(tmo, 1u); break; } } }
.LBB0_667:
	s_and_b32 s14, s11, 0xff
	s_mov_b64 s[20:21], -1
	s_cmp_lg_u32 s14, 0
	s_mov_b64 s[26:27], -1
	s_sleep 24
	s_cbranch_scc0 .LBB0_670
	s_and_b64 vcc, exec, s[26:27]
	s_cbranch_vccz .LBB0_666

; __device__ __forceinline__ unsigned xb_ld(unsigned* p)              { return __hip_atomic_load(p, __ATOMIC_RELAXED, __HIP_MEMORY_SCOPE_AGENT); }
; __device__ __forceinline__ void grp_barrier(unsigned* cntw, unsigned* tmo) {
;     ...
;         while (xb_ld(cntw) < target) { __builtin_amdgcn_s_sleep(1);
;             if ((++sp & 255u) == 0u) { if (xb_ld(tmo)) break; if (sp > XB_SPIN_CAP) { atomicAdd(tmo, 1u); break; } } }
.LBB0_902:
	s_and_b32 s24, s28, 0xff
	s_mov_b64 s[20:21], -1
	s_cmp_lg_u32 s24, 0
	s_mov_b64 s[26:27], -1
	s_sleep 24
	s_cbranch_scc0 .LBB0_905
	s_and_b64 vcc, exec, s[26:27]
	s_cbranch_vccz .LBB0_901
